# v39 + prologue rmsnorm row loop software-pipelined (next row's loads in flight while the current row is reduced)
# speedup vs baseline: 1.0187x; 1.0111x over previous
; DI void prologue(KArgs ap, int gw, int NGW, int lane) {
;     ...
;     {
;         f32x4 gg[4];
; #pragma unroll
;         for (int j = 0; j < 4; ++j) gg[j] = *((const f32x4*)g_attn + lane + 64 * j);
;         bf16_t* XN = (bf16_t*)(ws + WS_XN);
;         for (int m = gw; m < MTOK; m += NGW) {
;             const f32x4* xr = (const f32x4*)(m < SEQ ? xp + (size_t)m * DM : xs + (size_t)(m - SEQ) * DM) + lane;
;             f32x4 v[4]; float s = 0.f;
; #pragma unroll
;             for (int j = 0; j < 4; ++j) { v[j] = xr[64 * j]; s += (v[j][0] * v[j][0] + v[j][1] * v[j][1]) + (v[j][2] * v[j][2] + v[j][3] * v[j][3]); }
;             const float rstd = rsqrtf(wave_sum(s) * (1.f / DM) + EPS);
.LBB0_36:
	s_cmpk_lt_i32 s6, 0x4800
	s_cbranch_scc0 .Lbt_fill
	v_lshlrev_b32_e32 v18, 4, v190
	s_waitcnt lgkmcnt(0)
	global_load_dwordx4 v[0:3], v18, s[12:13]
	global_load_dwordx4 v[4:7], v18, s[12:13] offset:1024
	global_load_dwordx4 v[8:11], v18, s[12:13] offset:2048
	global_load_dwordx4 v[12:15], v18, s[12:13] offset:3072
	v_mbcnt_lo_u32_b32 v16, -1, 0
	v_mbcnt_hi_u32_b32 v16, -1, v16
	v_and_b32_e32 v17, 64, v16
	v_add_u32_e32 v17, 64, v17
	v_xor_b32_e32 v19, 1, v16
	v_cmp_lt_i32_e32 vcc, v19, v17
	v_xor_b32_e32 v20, 2, v16
	v_xor_b32_e32 v21, 4, v16
	v_cndmask_b32_e32 v19, v16, v19, vcc
	v_cmp_lt_i32_e32 vcc, v20, v17
	v_xor_b32_e32 v22, 8, v16
	v_xor_b32_e32 v23, 16, v16
	v_cndmask_b32_e32 v20, v16, v20, vcc
	v_cmp_lt_i32_e32 vcc, v21, v17
	v_xor_b32_e32 v24, 32, v16
	s_mov_b64 s[14:15], 0x9000000
	v_cndmask_b32_e32 v21, v16, v21, vcc
	v_cmp_lt_i32_e32 vcc, v22, v17
	s_ashr_i32 s7, s6, 31
	s_ashr_i32 s5, s4, 31
	v_cndmask_b32_e32 v22, v16, v22, vcc
	v_cmp_lt_i32_e32 vcc, v23, v17
	s_mov_b32 s13, 0
	v_lshlrev_b32_e32 v19, 2, v19
	v_cndmask_b32_e32 v23, v16, v23, vcc
	v_cmp_lt_i32_e32 vcc, v24, v17
	v_mov_b32_e32 v17, 0
	v_lshlrev_b32_e32 v20, 2, v20
	v_cndmask_b32_e32 v16, v16, v24, vcc
	v_lshlrev_b32_e32 v24, 2, v16
	v_lshlrev_b32_e32 v16, 3, v190
	v_lshl_add_u64 v[16:17], s[16:17], 0, v[16:17]
	v_lshl_add_u64 v[16:17], v[16:17], 0, s[14:15]
	s_lshl_b64 s[14:15], s[6:7], 12
	s_add_u32 s8, s8, s14
	v_lshlrev_b32_e32 v21, 2, v21
	v_lshlrev_b32_e32 v22, 2, v22
	v_lshlrev_b32_e32 v23, 2, v23
	s_addc_u32 s9, s9, s15
	s_lshl_b64 s[14:15], s[4:5], 12
	v_mov_b32_e32 v25, 0x358637bd
	s_mov_b32 s20, 0x800000
	s_branch .LBB0_39
.LBB0_39:
	s_cmpk_lt_i32 s6, 0x4000
	s_mov_b64 s[16:17], s[6:7]
	s_mov_b64 s[18:19], s[8:9]
	s_cbranch_scc1 .Lxn_ld0
	s_add_i32 s12, s6, 0xffffc000
	s_lshl_b64 s[16:17], s[12:13], 12
	s_add_u32 s18, s10, s16
	s_mov_b32 s12, s6
	s_addc_u32 s19, s11, s17
	s_mov_b64 s[16:17], s[12:13]
.Lxn_ld0:
	global_load_dwordx4 v[100:103], v18, s[18:19]
	global_load_dwordx4 v[104:107], v18, s[18:19] offset:1024
	global_load_dwordx4 v[108:111], v18, s[18:19] offset:3072
	global_load_dwordx4 v[112:115], v18, s[18:19] offset:2048
	s_waitcnt vmcnt(0)
	s_branch .Lxn_entry

; DI u32x2 pk4(f32x4 v) { u32x2 r; r.x = pk2(v[0], v[1]); r.y = pk2(v[2], v[3]); return r; }
; DI void prologue(KArgs ap, int gw, int NGW, int lane) {
;     ...
;         for (int m = gw; m < MTOK; m += NGW) {
;             const f32x4* xr = (const f32x4*)(m < SEQ ? xp + (size_t)m * DM : xs + (size_t)(m - SEQ) * DM) + lane;
;             f32x4 v[4]; float s = 0.f;
; #pragma unroll
;             for (int j = 0; j < 4; ++j) { v[j] = xr[64 * j]; s += (v[j][0] * v[j][0] + v[j][1] * v[j][1]) + (v[j][2] * v[j][2] + v[j][3] * v[j][3]); }
;             const float rstd = rsqrtf(wave_sum(s) * (1.f / DM) + EPS);
;             u32x2* o8 = (u32x2*)(XN + (size_t)m * DM) + lane;
; #pragma unroll
;             for (int j = 0; j < 4; ++j) o8[64 * j] = pk4(v[j] * rstd * gg[j]);
;         }
.Lxn_entry:
	v_mov_b64_e32 v[26:27], v[100:101]
	v_mov_b64_e32 v[28:29], v[102:103]
	v_mov_b64_e32 v[30:31], v[104:105]
	v_mov_b64_e32 v[32:33], v[106:107]
	v_mov_b64_e32 v[34:35], v[108:109]
	v_mov_b64_e32 v[36:37], v[110:111]
	v_mov_b64_e32 v[38:39], v[112:113]
	v_mov_b64_e32 v[40:41], v[114:115]
	s_lshl_b64 s[98:99], s[16:17], 11
	s_add_u32 s6, s6, s4
	s_addc_u32 s7, s7, s5
	s_add_u32 s8, s8, s14
	s_addc_u32 s9, s9, s15
	s_cmpk_lt_i32 s6, 0x4800
	s_cselect_b32 s32, 1, 0
	s_cbranch_scc0 .Lxn_nold
	s_cmpk_lt_i32 s6, 0x4000
	s_mov_b64 s[16:17], s[6:7]
	s_mov_b64 s[18:19], s[8:9]
	s_cbranch_scc1 .Lxn_ld
	s_add_i32 s12, s6, 0xffffc000
	s_lshl_b64 s[16:17], s[12:13], 12
	s_add_u32 s18, s10, s16
	s_mov_b32 s12, s6
	s_addc_u32 s19, s11, s17
	s_mov_b64 s[16:17], s[12:13]
.Lxn_ld:
	global_load_dwordx4 v[100:103], v18, s[18:19]
	global_load_dwordx4 v[104:107], v18, s[18:19] offset:1024
	global_load_dwordx4 v[108:111], v18, s[18:19] offset:3072
	global_load_dwordx4 v[112:115], v18, s[18:19] offset:2048
.Lxn_nold:
	v_pk_mul_f32 v[42:43], v[28:29], v[28:29]
	v_pk_mul_f32 v[44:45], v[26:27], v[26:27]
	v_pk_mul_f32 v[46:47], v[32:33], v[32:33]
	v_pk_mul_f32 v[48:49], v[30:31], v[30:31]
	v_pk_mov_b32 v[54:55], v[44:45], v[42:43] op_sel:[1,0]
	v_mov_b32_e32 v45, v43
	v_pk_mov_b32 v[42:43], v[48:49], v[46:47] op_sel:[1,0]
	v_mov_b32_e32 v49, v47
	v_mul_f32_e32 v53, v34, v34
	v_mul_f32_e32 v50, v39, v39
	v_mul_f32_e32 v52, v41, v41
	v_pk_add_f32 v[44:45], v[54:55], v[44:45]
	v_pk_add_f32 v[42:43], v[42:43], v[48:49]
	v_mul_f32_e32 v56, v35, v35
	v_mul_f32_e32 v57, v36, v36
	v_mul_f32_e32 v58, v37, v37
	v_pk_fma_f32 v[46:47], v[38:39], v[38:39], v[50:51] op_sel_hi:[1,1,0]
	v_pk_fma_f32 v[50:51], v[40:41], v[40:41], v[52:53] op_sel_hi:[1,1,0]
	v_pk_add_f32 v[44:45], v[44:45], v[44:45] op_sel:[0,1] op_sel_hi:[1,0]
	v_pk_add_f32 v[42:43], v[42:43], v[42:43] op_sel:[0,1] op_sel_hi:[1,0]
	v_mov_b32_e32 v47, v57
	v_mov_b32_e32 v51, v58
	v_mov_b32_e32 v45, v53
	v_mov_b32_e32 v43, v56
	v_pk_add_f32 v[46:47], v[46:47], v[50:51]
	v_pk_add_f32 v[42:43], v[44:45], v[42:43]
	s_nop 0
	v_pk_add_f32 v[42:43], v[42:43], v[46:47]
	s_nop 0
	v_add_f32_e32 v42, v42, v43
	ds_bpermute_b32 v43, v19, v42
	s_waitcnt lgkmcnt(0)
	v_add_f32_e32 v42, v42, v43
	ds_bpermute_b32 v43, v20, v42
	s_waitcnt lgkmcnt(0)
	v_add_f32_e32 v42, v42, v43
	ds_bpermute_b32 v43, v21, v42
	s_waitcnt lgkmcnt(0)
	v_add_f32_e32 v42, v42, v43
	ds_bpermute_b32 v43, v22, v42
	s_waitcnt lgkmcnt(0)
	v_add_f32_e32 v42, v42, v43
	ds_bpermute_b32 v43, v23, v42
	s_waitcnt lgkmcnt(0)
	v_add_f32_e32 v44, v42, v43
	ds_bpermute_b32 v45, v24, v44
	v_lshl_add_u64 v[42:43], v[16:17], 0, s[98:99]
	s_waitcnt lgkmcnt(0)
	v_add_f32_e32 v44, v44, v45
	v_fmamk_f32 v44, v44, 0x3a800000, v25
	v_mul_f32_e32 v45, 0x4b800000, v44
	v_cmp_gt_f32_e32 vcc, s20, v44
	s_nop 1
	v_cndmask_b32_e32 v44, v44, v45, vcc
	v_rsq_f32_e32 v44, v44
	s_nop 0
	v_mul_f32_e32 v45, 0x45800000, v44
	v_cndmask_b32_e32 v44, v44, v45, vcc
	v_pk_mul_f32 v[26:27], v[26:27], v[44:45] op_sel_hi:[1,0]
	v_pk_mul_f32 v[28:29], v[28:29], v[44:45] op_sel_hi:[1,0]
	v_pk_mul_f32 v[30:31], v[30:31], v[44:45] op_sel_hi:[1,0]
	v_pk_mul_f32 v[32:33], v[32:33], v[44:45] op_sel_hi:[1,0]
	v_pk_mul_f32 v[38:39], v[38:39], v[44:45] op_sel_hi:[1,0]
	v_pk_mul_f32 v[40:41], v[40:41], v[44:45] op_sel_hi:[1,0]
	v_pk_mul_f32 v[34:35], v[34:35], v[44:45] op_sel_hi:[1,0]
	v_pk_mul_f32 v[36:37], v[36:37], v[44:45] op_sel_hi:[1,0]
	v_pk_mul_f32 v[28:29], v[2:3], v[28:29]
	v_pk_mul_f32 v[26:27], v[0:1], v[26:27]
	v_pk_mul_f32 v[32:33], v[6:7], v[32:33]
	v_pk_mul_f32 v[30:31], v[4:5], v[30:31]
	v_pk_mul_f32 v[40:41], v[10:11], v[40:41]
	v_pk_mul_f32 v[38:39], v[8:9], v[38:39]
	v_pk_mul_f32 v[36:37], v[14:15], v[36:37]
	v_pk_mul_f32 v[34:35], v[12:13], v[34:35]
	v_cvt_pk_bf16_f32 v26, v26, v27
	v_cvt_pk_bf16_f32 v27, v28, v29
	v_cvt_pk_bf16_f32 v28, v30, v31
	v_cvt_pk_bf16_f32 v29, v32, v33
	v_cvt_pk_bf16_f32 v30, v38, v39
	v_cvt_pk_bf16_f32 v31, v40, v41
	v_cvt_pk_bf16_f32 v32, v34, v35
	v_cvt_pk_bf16_f32 v33, v36, v37
	global_store_dwordx2 v[42:43], v[26:27], off
	global_store_dwordx2 v[42:43], v[28:29], off offset:512
	global_store_dwordx2 v[42:43], v[30:31], off offset:1024
	global_store_dwordx2 v[42:43], v[32:33], off offset:1536
	s_cmp_lg_u32 s32, 0
	s_cbranch_scc1 .Lxn_top
	s_branch .Lbt_fill
	s_branch .Lbt_fill
